# in-projection and up K loops: after an epilogue the first two counted waits of the next tile no longer wait for that epilogue's stores
# baseline (speedup 1.0000x reference)
.LBB0_169:
	s_mov_b32 s84, 0
	s_lshl_b32 s5, s5, 5
	s_mov_b64 s[10:11], 0x80
	s_and_b32 s5, s5, 0x60
	s_add_i32 m0, s30, 0x18000
	v_lshl_add_u64 v[6:7], v[6:7], 0, s[10:11]
	s_lshl_b32 s7, s4, 13
	s_lshl_b32 s9, s5, 7
	s_waitcnt vmcnt(2)
	s_barrier
	global_load_lds_dwordx4 v[6:7], off
	v_lshl_add_u64 v[4:5], v[4:5], 0, s[10:11]
	s_add_i32 m0, s30, 0x1a000
	s_add_i32 s38, s30, 0x8000
	s_add_i32 s39, s30, 0xa000
	global_load_lds_dwordx4 v[4:5], off
	v_lshl_add_u64 v[2:3], v[2:3], 0, s[10:11]
	s_mov_b32 m0, s38
	s_add_u32 s12, s26, 0x40080
	global_load_lds_dwordx4 v[2:3], off
	v_lshl_add_u64 v[0:1], v[0:1], 0, s[10:11]
	s_mov_b32 m0, s39
	s_addc_u32 s13, s27, 0
	global_load_lds_dwordx4 v[0:1], off
	s_add_i32 m0, s30, 0x1c000
	v_lshl_add_u64 v[0:1], s[12:13], 0, v[130:131]
	global_load_lds_dwordx4 v[0:1], off
	v_lshl_add_u64 v[0:1], s[12:13], 0, v[134:135]
	s_add_i32 m0, s30, 0x1e000
	v_readlane_b32 s16, v252, 0
	global_load_lds_dwordx4 v[0:1], off
	v_lshrrev_b32_e32 v1, 1, v8
	v_and_b32_e32 v1, 24, v1
	v_and_b32_e32 v0, 15, v8
	v_lshlrev_b32_e32 v2, 1, v1
	v_lshl_or_b32 v160, s4, 6, v0
	v_lshl_or_b32 v0, v0, 6, v2
	v_lshlrev_b32_e32 v2, 2, v8
	v_and_b32_e32 v2, 32, v2
	v_bitop3_b32 v3, v0, s7, v2 bitop3:0xde
	v_bitop3_b32 v161, v0, s9, v2 bitop3:0xde
	v_lshlrev_b32_e32 v0, 14, v9
	v_and_b32_e32 v0, 0xffff8000, v0
	v_or_b32_e32 v162, s5, v1
	v_lshl_add_u32 v0, v10, 11, v0
	v_and_b32_e32 v1, 1, v9
	s_cmpk_lt_u32 s2, 0x100
	v_readlane_b32 s22, v252, 6
	v_lshl_or_b32 v0, v1, 6, v0
	s_cselect_b64 s[12:13], -1, 0
	v_readlane_b32 s23, v252, 7
	s_add_u32 s14, s22, 0x2120000
	v_lshl_add_u32 v142, v11, 1, v0
	v_lshlrev_b32_e32 v0, 14, v12
	s_addc_u32 s15, s23, 0
	v_and_b32_e32 v0, 0xffff8000, v0
	s_waitcnt vmcnt(6)
	s_add_u32 s40, s22, 0x5180000
	v_lshl_add_u32 v0, v13, 11, v0
	v_and_b32_e32 v1, 1, v12
	s_addc_u32 s41, s23, 0
	v_lshlrev_b32_e32 v136, 1, v162
	v_lshl_or_b32 v0, v1, 6, v0
	s_add_i32 s45, 0, 0x10000
	s_add_i32 s46, 0, 0x14000
	v_lshrrev_b32_e32 v138, 1, v162
	v_readlane_b32 s18, v252, 2
	v_lshl_add_u64 v[140:141], s[22:23], 0, v[136:137]
	s_ashr_i32 s42, s86, 31
	s_mov_b32 s43, s86
	s_ashr_i32 s44, s54, 31
	v_mov_b32_e32 v143, v137
	v_lshl_add_u32 v144, v14, 1, v0
	v_mov_b32_e32 v145, v137
	v_mov_b64_e32 v[146:147], 0x600
	v_mov_b64_e32 v[148:149], 0x5ff
	v_add_u32_e32 v163, s45, v161
	v_add_u32_e32 v164, s46, v161
	v_add_u32_e32 v165, 0, v3
	s_movk_i32 s47, 0x3ff
	s_movk_i32 s48, 0xfa00
	s_mov_b32 s49, 0x1020000
	v_mov_b32_e32 v166, 0x46800000
	v_mov_b32_e32 v167, 0x3db504f3
	s_barrier
	v_readlane_b32 s17, v252, 1
	v_readlane_b32 s19, v252, 3
	v_readlane_b32 s20, v252, 4
	v_readlane_b32 s21, v252, 5
	s_branch .LBB0_172

.LBB0_175:
	ds_read_b128 v[150:153], v163
	ds_read_b128 v[154:157], v163 offset:1024
	ds_read_b128 v[168:171], v163 offset:2048
	ds_read_b128 v[172:175], v163 offset:3072
	ds_read_b128 v[178:181], v164
	ds_read_b128 v[182:185], v164 offset:1024
	ds_read_b128 v[186:189], v164 offset:2048
	ds_read_b128 v[190:193], v164 offset:3072
	s_add_u32 s26, s24, 0xfffc0080
	s_addc_u32 s27, s25, -1
	s_cmp_eq_u32 s50, 12
	s_cselect_b32 s29, s2, s27
	s_cselect_b32 s28, s7, s26
	s_cselect_b32 s27, s9, s33
	s_cselect_b32 s26, s17, s19
	v_lshl_add_u64 v[158:159], s[24:25], 0, v[142:143]
	s_add_i32 m0, s30, 0xc000
	ds_read_b128 v[194:197], v165
	ds_read_b128 v[198:201], v165 offset:1024
	ds_read_b128 v[202:205], v165 offset:2048
	ds_read_b128 v[206:209], v165 offset:3072
	ds_read_b128 v[210:213], v165 offset:4096
	ds_read_b128 v[214:217], v165 offset:5120
	ds_read_b128 v[218:221], v165 offset:6144
	ds_read_b128 v[222:225], v165 offset:7168
	global_load_lds_dwordx4 v[158:159], off
	v_lshl_add_u64 v[158:159], s[24:25], 0, v[144:145]
	s_add_i32 m0, s30, 0xe000
	s_nop 0
	global_load_lds_dwordx4 v[158:159], off
	s_cmp_eq_u32 s84, 0
	s_cbranch_scc1 .Lrxi1_s
	s_waitcnt vmcnt(16)
	s_branch .Lrxi1_d
.Lrxi1_s:
	s_waitcnt vmcnt(8)
.Lrxi1_d:
	s_waitcnt lgkmcnt(0)
	s_barrier
	s_setprio 1
	s_waitcnt lgkmcnt(0)
	v_mfma_f32_16x16x32_bf16 v[124:127], v[150:153], v[194:197], v[124:127]
	v_mfma_f32_16x16x32_bf16 v[120:123], v[168:171], v[194:197], v[120:123]
	v_mfma_f32_16x16x32_bf16 v[108:111], v[150:153], v[202:205], v[108:111]
	v_mfma_f32_16x16x32_bf16 v[104:107], v[168:171], v[202:205], v[104:107]
	v_mfma_f32_16x16x32_bf16 v[92:95], v[150:153], v[210:213], v[92:95]
	v_mfma_f32_16x16x32_bf16 v[88:91], v[168:171], v[210:213], v[88:91]
	v_mfma_f32_16x16x32_bf16 v[76:79], v[150:153], v[218:221], v[76:79]
	v_mfma_f32_16x16x32_bf16 v[72:75], v[168:171], v[218:221], v[72:75]
	v_mfma_f32_16x16x32_bf16 v[124:127], v[154:157], v[198:201], v[124:127]
	v_mfma_f32_16x16x32_bf16 v[120:123], v[172:175], v[198:201], v[120:123]
	v_mfma_f32_16x16x32_bf16 v[108:111], v[154:157], v[206:209], v[108:111]
	v_mfma_f32_16x16x32_bf16 v[104:107], v[172:175], v[206:209], v[104:107]
	v_mfma_f32_16x16x32_bf16 v[92:95], v[154:157], v[214:217], v[92:95]
	v_mfma_f32_16x16x32_bf16 v[88:91], v[172:175], v[214:217], v[88:91]
	v_mfma_f32_16x16x32_bf16 v[76:79], v[154:157], v[222:225], v[76:79]
	v_mfma_f32_16x16x32_bf16 v[72:75], v[172:175], v[222:225], v[72:75]
	s_setprio 0
	s_setprio 1
	v_mfma_f32_16x16x32_bf16 v[116:119], v[178:181], v[194:197], v[116:119]
	v_mfma_f32_16x16x32_bf16 v[112:115], v[186:189], v[194:197], v[112:115]
	v_mfma_f32_16x16x32_bf16 v[100:103], v[178:181], v[202:205], v[100:103]
	v_mfma_f32_16x16x32_bf16 v[96:99], v[186:189], v[202:205], v[96:99]
	v_mfma_f32_16x16x32_bf16 v[84:87], v[178:181], v[210:213], v[84:87]
	v_mfma_f32_16x16x32_bf16 v[80:83], v[186:189], v[210:213], v[80:83]
	v_mfma_f32_16x16x32_bf16 v[68:71], v[178:181], v[218:221], v[68:71]
	v_mfma_f32_16x16x32_bf16 v[64:67], v[186:189], v[218:221], v[64:67]
	v_mfma_f32_16x16x32_bf16 v[116:119], v[182:185], v[198:201], v[116:119]
	v_mfma_f32_16x16x32_bf16 v[112:115], v[190:193], v[198:201], v[112:115]
	v_mfma_f32_16x16x32_bf16 v[100:103], v[182:185], v[206:209], v[100:103]
	v_mfma_f32_16x16x32_bf16 v[96:99], v[190:193], v[206:209], v[96:99]
	v_mfma_f32_16x16x32_bf16 v[84:87], v[182:185], v[214:217], v[84:87]
	v_mfma_f32_16x16x32_bf16 v[80:83], v[190:193], v[214:217], v[80:83]
	v_mfma_f32_16x16x32_bf16 v[68:71], v[182:185], v[222:225], v[68:71]
	v_mfma_f32_16x16x32_bf16 v[64:67], v[190:193], v[222:225], v[64:67]
	s_setprio 0
	s_barrier
	s_add_i32 s51, s45, s3
	v_lshl_add_u64 v[158:159], s[26:27], 0, v[130:131]
	s_mov_b32 m0, s51
	ds_read_b128 v[194:197], v165 offset:16384
	ds_read_b128 v[198:201], v165 offset:17408
	ds_read_b128 v[202:205], v165 offset:18432
	ds_read_b128 v[206:209], v165 offset:19456
	ds_read_b128 v[210:213], v165 offset:20480
	ds_read_b128 v[214:217], v165 offset:21504
	ds_read_b128 v[218:221], v165 offset:22528
	ds_read_b128 v[222:225], v165 offset:23552
	global_load_lds_dwordx4 v[158:159], off
	s_add_i32 m0, s51, 0x2000
	s_add_u32 s52, s26, 0x40000
	v_lshl_add_u64 v[226:227], s[26:27], 0, v[134:135]
	s_addc_u32 s53, s27, 0
	s_add_i32 s51, s46, s3
	global_load_lds_dwordx4 v[226:227], off
	v_lshl_add_u64 v[228:229], s[52:53], 0, v[130:131]
	s_mov_b32 m0, s51
	v_lshl_add_u64 v[230:231], s[28:29], 0, v[132:133]
	global_load_lds_dwordx4 v[228:229], off
	v_lshl_add_u64 v[228:229], s[52:53], 0, v[134:135]
	s_add_i32 m0, s51, 0x2000
	s_nop 0
	global_load_lds_dwordx4 v[228:229], off
	v_lshl_add_u64 v[228:229], s[28:29], 0, v[128:129]
	s_mov_b32 m0, s30
	s_nop 0
	global_load_lds_dwordx4 v[228:229], off
	s_mov_b32 m0, s31
	s_nop 0
	global_load_lds_dwordx4 v[230:231], off
	s_cmp_eq_u32 s84, 0
	s_cbranch_scc1 .Lrxi2_s
	s_waitcnt vmcnt(22)
	s_mov_b32 s84, 0
	s_branch .Lrxi2_d

.Lrxi2_d:
	s_waitcnt lgkmcnt(0)
	s_barrier
	s_setprio 1
	s_waitcnt lgkmcnt(0)
	v_mfma_f32_16x16x32_bf16 v[60:63], v[150:153], v[194:197], v[60:63]
	v_mfma_f32_16x16x32_bf16 v[56:59], v[168:171], v[194:197], v[56:59]
	v_mfma_f32_16x16x32_bf16 v[44:47], v[150:153], v[202:205], v[44:47]
	v_mfma_f32_16x16x32_bf16 v[40:43], v[168:171], v[202:205], v[40:43]
	v_mfma_f32_16x16x32_bf16 v[28:31], v[150:153], v[210:213], v[28:31]
	v_mfma_f32_16x16x32_bf16 v[24:27], v[168:171], v[210:213], v[24:27]
	v_mfma_f32_16x16x32_bf16 v[12:15], v[150:153], v[218:221], v[12:15]
	v_mfma_f32_16x16x32_bf16 v[8:11], v[168:171], v[218:221], v[8:11]
	v_mfma_f32_16x16x32_bf16 v[60:63], v[154:157], v[198:201], v[60:63]
	v_mfma_f32_16x16x32_bf16 v[56:59], v[172:175], v[198:201], v[56:59]
	v_mfma_f32_16x16x32_bf16 v[44:47], v[154:157], v[206:209], v[44:47]
	v_mfma_f32_16x16x32_bf16 v[40:43], v[172:175], v[206:209], v[40:43]
	v_mfma_f32_16x16x32_bf16 v[28:31], v[154:157], v[214:217], v[28:31]
	v_mfma_f32_16x16x32_bf16 v[24:27], v[172:175], v[214:217], v[24:27]
	v_mfma_f32_16x16x32_bf16 v[12:15], v[154:157], v[222:225], v[12:15]
	v_mfma_f32_16x16x32_bf16 v[8:11], v[172:175], v[222:225], v[8:11]
	s_setprio 0
	s_setprio 1
	v_mfma_f32_16x16x32_bf16 v[52:55], v[178:181], v[194:197], v[52:55]
	v_mfma_f32_16x16x32_bf16 v[48:51], v[186:189], v[194:197], v[48:51]
	v_mfma_f32_16x16x32_bf16 v[36:39], v[178:181], v[202:205], v[36:39]
	v_mfma_f32_16x16x32_bf16 v[32:35], v[186:189], v[202:205], v[32:35]
	v_mfma_f32_16x16x32_bf16 v[20:23], v[178:181], v[210:213], v[20:23]
	v_mfma_f32_16x16x32_bf16 v[16:19], v[186:189], v[210:213], v[16:19]
	v_mfma_f32_16x16x32_bf16 v[4:7], v[178:181], v[218:221], v[4:7]
	v_mfma_f32_16x16x32_bf16 v[0:3], v[186:189], v[218:221], v[0:3]
	v_mfma_f32_16x16x32_bf16 v[52:55], v[182:185], v[198:201], v[52:55]
	v_mfma_f32_16x16x32_bf16 v[48:51], v[190:193], v[198:201], v[48:51]
	v_mfma_f32_16x16x32_bf16 v[36:39], v[182:185], v[206:209], v[36:39]
	v_mfma_f32_16x16x32_bf16 v[32:35], v[190:193], v[206:209], v[32:35]
	v_mfma_f32_16x16x32_bf16 v[20:23], v[182:185], v[214:217], v[20:23]
	v_mfma_f32_16x16x32_bf16 v[16:19], v[190:193], v[214:217], v[16:19]
	v_mfma_f32_16x16x32_bf16 v[4:7], v[182:185], v[222:225], v[4:7]
	v_mfma_f32_16x16x32_bf16 v[0:3], v[190:193], v[222:225], v[0:3]
	s_setprio 0
	s_barrier
	s_add_i32 s51, 0, 0x18000
	v_add_u32_e32 v136, s51, v161
	s_add_i32 s52, 0, 0x1c000
	ds_read_b128 v[150:153], v136
	ds_read_b128 v[154:157], v136 offset:1024
	ds_read_b128 v[168:171], v136 offset:2048
	ds_read_b128 v[172:175], v136 offset:3072
	v_add_u32_e32 v136, s52, v161
	ds_read_b128 v[178:181], v136
	ds_read_b128 v[182:185], v136 offset:1024
	ds_read_b128 v[186:189], v136 offset:2048
	ds_read_b128 v[190:193], v136 offset:3072
	s_add_u32 s28, s28, 0x40000
	s_addc_u32 s29, s29, 0
	s_mov_b32 m0, s34
	v_lshl_add_u64 v[232:233], s[28:29], 0, v[128:129]
	ds_read_b128 v[194:197], v165 offset:32768
	ds_read_b128 v[198:201], v165 offset:33792
	ds_read_b128 v[202:205], v165 offset:34816
	ds_read_b128 v[206:209], v165 offset:35840
	ds_read_b128 v[210:213], v165 offset:36864
	ds_read_b128 v[214:217], v165 offset:37888
	ds_read_b128 v[218:221], v165 offset:38912
	ds_read_b128 v[222:225], v165 offset:39936
	global_load_lds_dwordx4 v[232:233], off
	v_lshl_add_u64 v[232:233], s[28:29], 0, v[132:133]
	s_mov_b32 m0, s35
	s_nop 0
	global_load_lds_dwordx4 v[232:233], off
	s_waitcnt vmcnt(8)
	s_waitcnt lgkmcnt(0)
	s_barrier
	s_setprio 1
	s_waitcnt lgkmcnt(0)
	v_mfma_f32_16x16x32_bf16 v[124:127], v[150:153], v[194:197], v[124:127]
	v_mfma_f32_16x16x32_bf16 v[120:123], v[168:171], v[194:197], v[120:123]
	v_mfma_f32_16x16x32_bf16 v[108:111], v[150:153], v[202:205], v[108:111]
	v_mfma_f32_16x16x32_bf16 v[104:107], v[168:171], v[202:205], v[104:107]
	v_mfma_f32_16x16x32_bf16 v[92:95], v[150:153], v[210:213], v[92:95]
	v_mfma_f32_16x16x32_bf16 v[88:91], v[168:171], v[210:213], v[88:91]
	v_mfma_f32_16x16x32_bf16 v[76:79], v[150:153], v[218:221], v[76:79]
	v_mfma_f32_16x16x32_bf16 v[72:75], v[168:171], v[218:221], v[72:75]
	v_mfma_f32_16x16x32_bf16 v[124:127], v[154:157], v[198:201], v[124:127]
	v_mfma_f32_16x16x32_bf16 v[120:123], v[172:175], v[198:201], v[120:123]
	v_mfma_f32_16x16x32_bf16 v[108:111], v[154:157], v[206:209], v[108:111]
	v_mfma_f32_16x16x32_bf16 v[104:107], v[172:175], v[206:209], v[104:107]
	v_mfma_f32_16x16x32_bf16 v[92:95], v[154:157], v[214:217], v[92:95]
	v_mfma_f32_16x16x32_bf16 v[88:91], v[172:175], v[214:217], v[88:91]
	v_mfma_f32_16x16x32_bf16 v[76:79], v[154:157], v[222:225], v[76:79]
	v_mfma_f32_16x16x32_bf16 v[72:75], v[172:175], v[222:225], v[72:75]
	s_setprio 0
	s_setprio 1
	v_mfma_f32_16x16x32_bf16 v[116:119], v[178:181], v[194:197], v[116:119]
	v_mfma_f32_16x16x32_bf16 v[112:115], v[186:189], v[194:197], v[112:115]
	v_mfma_f32_16x16x32_bf16 v[100:103], v[178:181], v[202:205], v[100:103]
	v_mfma_f32_16x16x32_bf16 v[96:99], v[186:189], v[202:205], v[96:99]
	v_mfma_f32_16x16x32_bf16 v[84:87], v[178:181], v[210:213], v[84:87]
	v_mfma_f32_16x16x32_bf16 v[80:83], v[186:189], v[210:213], v[80:83]
	v_mfma_f32_16x16x32_bf16 v[68:71], v[178:181], v[218:221], v[68:71]
	v_mfma_f32_16x16x32_bf16 v[64:67], v[186:189], v[218:221], v[64:67]
	v_mfma_f32_16x16x32_bf16 v[116:119], v[182:185], v[198:201], v[116:119]
	v_mfma_f32_16x16x32_bf16 v[112:115], v[190:193], v[198:201], v[112:115]
	v_mfma_f32_16x16x32_bf16 v[100:103], v[182:185], v[206:209], v[100:103]
	v_mfma_f32_16x16x32_bf16 v[96:99], v[190:193], v[206:209], v[96:99]
	v_mfma_f32_16x16x32_bf16 v[84:87], v[182:185], v[214:217], v[84:87]
	v_mfma_f32_16x16x32_bf16 v[80:83], v[190:193], v[214:217], v[80:83]
	v_mfma_f32_16x16x32_bf16 v[68:71], v[182:185], v[222:225], v[68:71]
	v_mfma_f32_16x16x32_bf16 v[64:67], v[190:193], v[222:225], v[64:67]
	s_setprio 0
	s_barrier
	s_add_i32 s28, s51, s3
	v_lshl_add_u64 v[158:159], v[158:159], 0, s[10:11]
	s_mov_b32 m0, s28
	ds_read_b128 v[194:197], v165 offset:49152
	ds_read_b128 v[198:201], v165 offset:50176
	ds_read_b128 v[202:205], v165 offset:51200
	ds_read_b128 v[206:209], v165 offset:52224
	ds_read_b128 v[210:213], v165 offset:53248
	ds_read_b128 v[214:217], v165 offset:54272
	ds_read_b128 v[218:221], v165 offset:55296
	ds_read_b128 v[222:225], v165 offset:56320
	global_load_lds_dwordx4 v[158:159], off
	s_add_i32 m0, s28, 0x2000
	s_add_u32 s26, s26, 0x40080
	v_lshl_add_u64 v[158:159], v[226:227], 0, s[10:11]
	s_addc_u32 s27, s27, 0
	s_add_i32 s28, s52, s3
	global_load_lds_dwordx4 v[158:159], off
	v_lshl_add_u64 v[158:159], s[26:27], 0, v[130:131]
	s_mov_b32 m0, s28
	s_nop 0
	global_load_lds_dwordx4 v[158:159], off
	v_lshl_add_u64 v[158:159], s[26:27], 0, v[134:135]
	s_add_i32 m0, s28, 0x2000
	s_nop 0
	global_load_lds_dwordx4 v[158:159], off
	v_lshl_add_u64 v[158:159], v[228:229], 0, s[10:11]
	s_mov_b32 m0, s38
	s_nop 0
	global_load_lds_dwordx4 v[158:159], off
	v_lshl_add_u64 v[158:159], v[230:231], 0, s[10:11]
	s_mov_b32 m0, s39
	s_nop 0
	global_load_lds_dwordx4 v[158:159], off
	s_waitcnt vmcnt(8)
	s_waitcnt lgkmcnt(0)
	s_barrier
	s_setprio 1
	s_waitcnt lgkmcnt(0)
	v_mfma_f32_16x16x32_bf16 v[60:63], v[150:153], v[194:197], v[60:63]
	v_mfma_f32_16x16x32_bf16 v[56:59], v[168:171], v[194:197], v[56:59]
	v_mfma_f32_16x16x32_bf16 v[44:47], v[150:153], v[202:205], v[44:47]
	v_mfma_f32_16x16x32_bf16 v[40:43], v[168:171], v[202:205], v[40:43]
	v_mfma_f32_16x16x32_bf16 v[28:31], v[150:153], v[210:213], v[28:31]
	v_mfma_f32_16x16x32_bf16 v[24:27], v[168:171], v[210:213], v[24:27]
	v_mfma_f32_16x16x32_bf16 v[12:15], v[150:153], v[218:221], v[12:15]
	v_mfma_f32_16x16x32_bf16 v[8:11], v[168:171], v[218:221], v[8:11]
	v_mfma_f32_16x16x32_bf16 v[60:63], v[154:157], v[198:201], v[60:63]
	v_mfma_f32_16x16x32_bf16 v[56:59], v[172:175], v[198:201], v[56:59]
	v_mfma_f32_16x16x32_bf16 v[44:47], v[154:157], v[206:209], v[44:47]
	v_mfma_f32_16x16x32_bf16 v[40:43], v[172:175], v[206:209], v[40:43]
	v_mfma_f32_16x16x32_bf16 v[28:31], v[154:157], v[214:217], v[28:31]
	v_mfma_f32_16x16x32_bf16 v[24:27], v[172:175], v[214:217], v[24:27]
	v_mfma_f32_16x16x32_bf16 v[12:15], v[154:157], v[222:225], v[12:15]
	v_mfma_f32_16x16x32_bf16 v[8:11], v[172:175], v[222:225], v[8:11]
	s_setprio 0
	s_setprio 1
	v_mfma_f32_16x16x32_bf16 v[52:55], v[178:181], v[194:197], v[52:55]
	v_mfma_f32_16x16x32_bf16 v[48:51], v[186:189], v[194:197], v[48:51]
	v_mfma_f32_16x16x32_bf16 v[36:39], v[178:181], v[202:205], v[36:39]
	v_mfma_f32_16x16x32_bf16 v[32:35], v[186:189], v[202:205], v[32:35]
	v_mfma_f32_16x16x32_bf16 v[20:23], v[178:181], v[210:213], v[20:23]
	v_mfma_f32_16x16x32_bf16 v[16:19], v[186:189], v[210:213], v[16:19]
	v_mfma_f32_16x16x32_bf16 v[4:7], v[178:181], v[218:221], v[4:7]
	v_mfma_f32_16x16x32_bf16 v[0:3], v[186:189], v[218:221], v[0:3]
	v_mfma_f32_16x16x32_bf16 v[52:55], v[182:185], v[198:201], v[52:55]
	v_mfma_f32_16x16x32_bf16 v[48:51], v[190:193], v[198:201], v[48:51]
	v_mfma_f32_16x16x32_bf16 v[36:39], v[182:185], v[206:209], v[36:39]
	v_mfma_f32_16x16x32_bf16 v[32:35], v[190:193], v[206:209], v[32:35]
	v_mfma_f32_16x16x32_bf16 v[20:23], v[182:185], v[214:217], v[20:23]
	v_mfma_f32_16x16x32_bf16 v[16:19], v[190:193], v[214:217], v[16:19]
	v_mfma_f32_16x16x32_bf16 v[4:7], v[182:185], v[222:225], v[4:7]
	v_mfma_f32_16x16x32_bf16 v[0:3], v[190:193], v[222:225], v[0:3]
	s_setprio 0
	s_barrier
	s_add_i32 s50, s50, 2
	s_add_u32 s24, s24, 0x100
	s_addc_u32 s25, s25, 0
	s_add_u32 s19, s19, 0x100
	s_addc_u32 s33, s33, 0
	s_cmp_gt_u32 s50, 13
	s_cbranch_scc0 .LBB0_175
	s_and_b64 vcc, exec, s[12:13]
	s_cbranch_vccz .LBB0_178
	s_barrier

.LBB0_290:
	s_mov_b32 s84, 1
	s_or_b64 exec, exec, s[6:7]
	s_andn2_b64 vcc, exec, s[4:5]
	s_mov_b64 s[4:5], -1
	s_cbranch_vccnz .LBB0_171
	s_andn2_b64 vcc, exec, s[0:1]
	s_cbranch_vccnz .LBB0_170
	s_barrier
	s_branch .LBB0_170

.Lxb5_end:
.LBB0_1060:
	s_mov_b32 s84, 0
	s_mov_b32 s100, 0
	s_or_b64 exec, exec, s[0:1]
	v_readlane_b32 s8, v252, 0
	v_readlane_b32 s9, v252, 1
	v_readlane_b32 s10, v252, 2
	v_readlane_b32 s11, v252, 3
	v_readlane_b32 s12, v252, 4
	v_readlane_b32 s13, v252, 5
	v_readlane_b32 s14, v252, 6
	v_readlane_b32 s15, v252, 7
	s_mov_b64 s[8:9], s[12:13]
	s_mov_b64 s[10:11], s[14:15]
	s_add_u32 s8, s10, 0x4160000
	s_addc_u32 s9, s11, 0
	v_mov_b32_e32 v9, v176
	s_waitcnt lgkmcnt(0)
	s_barrier
	s_cmpk_gt_i32 s72, 0x3ff
	v_readfirstlane_b32 s7, v9
	s_cbranch_scc1 .LBB0_1086
	s_ashr_i32 s2, s72, 31
	s_lshr_b32 s0, s2, 29
	s_add_i32 s3, s72, s0
	s_and_b32 s0, s3, -8
	s_sub_i32 s10, s72, s0
	s_cmp_gt_i32 s10, -1
	s_cbranch_scc0 .LBB0_1063
	s_lshl_b32 s6, s10, 7
	s_cbranch_execz .LBB0_1064
	s_branch .LBB0_1065

.LBB0_1079:
	ds_read_b128 v[156:159], v150
	ds_read_b128 v[160:163], v150 offset:1024
	ds_read_b128 v[164:167], v150 offset:2048
	ds_read_b128 v[168:171], v150 offset:3072
	ds_read_b128 v[172:175], v151
	ds_read_b128 v[178:181], v151 offset:1024
	ds_read_b128 v[182:185], v151 offset:2048
	ds_read_b128 v[186:189], v151 offset:3072
	s_add_u32 s34, s30, 0xfffc0080
	s_addc_u32 s35, s31, -1
	s_cmp_eq_u32 s54, 12
	s_cselect_b32 s37, s23, s35
	s_cselect_b32 s36, s50, s34
	s_cselect_b32 s35, s17, s53
	s_cselect_b32 s34, s51, s52
	v_lshl_add_u64 v[144:145], s[30:31], 0, v[136:137]
	s_add_i32 m0, s29, 0xc000
	ds_read_b128 v[190:193], v152
	ds_read_b128 v[194:197], v152 offset:1024
	ds_read_b128 v[198:201], v152 offset:2048
	ds_read_b128 v[202:205], v152 offset:3072
	ds_read_b128 v[206:209], v152 offset:4096
	ds_read_b128 v[210:213], v152 offset:5120
	ds_read_b128 v[214:217], v152 offset:6144
	ds_read_b128 v[218:221], v152 offset:7168
	global_load_lds_dwordx4 v[144:145], off
	v_lshl_add_u64 v[144:145], s[30:31], 0, v[138:139]
	s_add_i32 m0, s29, 0xe000
	s_nop 0
	global_load_lds_dwordx4 v[144:145], off
	s_cmp_eq_u32 s84, 0
	s_cbranch_scc1 .Lrxu1_s
	s_waitcnt vmcnt(16)
	s_branch .Lrxu1_d

.Lrxu1_d:
	s_waitcnt lgkmcnt(0)
	s_barrier
	s_setprio 1
	s_waitcnt lgkmcnt(0)
	v_mfma_f32_16x16x32_bf16 v[124:127], v[156:159], v[190:193], v[124:127]
	v_mfma_f32_16x16x32_bf16 v[120:123], v[164:167], v[190:193], v[120:123]
	v_mfma_f32_16x16x32_bf16 v[108:111], v[156:159], v[198:201], v[108:111]
	v_mfma_f32_16x16x32_bf16 v[104:107], v[164:167], v[198:201], v[104:107]
	v_mfma_f32_16x16x32_bf16 v[92:95], v[156:159], v[206:209], v[92:95]
	v_mfma_f32_16x16x32_bf16 v[88:91], v[164:167], v[206:209], v[88:91]
	v_mfma_f32_16x16x32_bf16 v[76:79], v[156:159], v[214:217], v[76:79]
	v_mfma_f32_16x16x32_bf16 v[72:75], v[164:167], v[214:217], v[72:75]
	v_mfma_f32_16x16x32_bf16 v[124:127], v[160:163], v[194:197], v[124:127]
	v_mfma_f32_16x16x32_bf16 v[120:123], v[168:171], v[194:197], v[120:123]
	v_mfma_f32_16x16x32_bf16 v[108:111], v[160:163], v[202:205], v[108:111]
	v_mfma_f32_16x16x32_bf16 v[104:107], v[168:171], v[202:205], v[104:107]
	v_mfma_f32_16x16x32_bf16 v[92:95], v[160:163], v[210:213], v[92:95]
	v_mfma_f32_16x16x32_bf16 v[88:91], v[168:171], v[210:213], v[88:91]
	v_mfma_f32_16x16x32_bf16 v[76:79], v[160:163], v[218:221], v[76:79]
	v_mfma_f32_16x16x32_bf16 v[72:75], v[168:171], v[218:221], v[72:75]
	s_setprio 0
	s_setprio 1
	v_mfma_f32_16x16x32_bf16 v[116:119], v[172:175], v[190:193], v[116:119]
	v_mfma_f32_16x16x32_bf16 v[112:115], v[182:185], v[190:193], v[112:115]
	v_mfma_f32_16x16x32_bf16 v[100:103], v[172:175], v[198:201], v[100:103]
	v_mfma_f32_16x16x32_bf16 v[96:99], v[182:185], v[198:201], v[96:99]
	v_mfma_f32_16x16x32_bf16 v[84:87], v[172:175], v[206:209], v[84:87]
	v_mfma_f32_16x16x32_bf16 v[80:83], v[182:185], v[206:209], v[80:83]
	v_mfma_f32_16x16x32_bf16 v[68:71], v[172:175], v[214:217], v[68:71]
	v_mfma_f32_16x16x32_bf16 v[64:67], v[182:185], v[214:217], v[64:67]
	v_mfma_f32_16x16x32_bf16 v[116:119], v[178:181], v[194:197], v[116:119]
	v_mfma_f32_16x16x32_bf16 v[112:115], v[186:189], v[194:197], v[112:115]
	v_mfma_f32_16x16x32_bf16 v[100:103], v[178:181], v[202:205], v[100:103]
	v_mfma_f32_16x16x32_bf16 v[96:99], v[186:189], v[202:205], v[96:99]
	v_mfma_f32_16x16x32_bf16 v[84:87], v[178:181], v[210:213], v[84:87]
	v_mfma_f32_16x16x32_bf16 v[80:83], v[186:189], v[210:213], v[80:83]
	v_mfma_f32_16x16x32_bf16 v[68:71], v[178:181], v[218:221], v[68:71]
	v_mfma_f32_16x16x32_bf16 v[64:67], v[186:189], v[218:221], v[64:67]
	s_setprio 0
	s_barrier
	s_add_i32 s55, s45, s3
	v_lshl_add_u64 v[144:145], s[34:35], 0, v[130:131]
	s_mov_b32 m0, s55
	ds_read_b128 v[190:193], v152 offset:16384
	ds_read_b128 v[194:197], v152 offset:17408
	ds_read_b128 v[198:201], v152 offset:18432
	ds_read_b128 v[202:205], v152 offset:19456
	ds_read_b128 v[206:209], v152 offset:20480
	ds_read_b128 v[210:213], v152 offset:21504
	ds_read_b128 v[214:217], v152 offset:22528
	ds_read_b128 v[218:221], v152 offset:23552
	global_load_lds_dwordx4 v[144:145], off
	s_add_i32 m0, s55, 0x2000
	s_add_u32 s56, s34, 0x40000
	v_lshl_add_u64 v[222:223], s[34:35], 0, v[134:135]
	s_addc_u32 s57, s35, 0
	s_add_i32 s55, s46, s3
	global_load_lds_dwordx4 v[222:223], off
	v_lshl_add_u64 v[224:225], s[56:57], 0, v[130:131]
	s_mov_b32 m0, s55
	v_lshl_add_u64 v[226:227], s[36:37], 0, v[132:133]
	global_load_lds_dwordx4 v[224:225], off
	v_lshl_add_u64 v[224:225], s[56:57], 0, v[134:135]
	s_add_i32 m0, s55, 0x2000
	s_nop 0
	global_load_lds_dwordx4 v[224:225], off
	v_lshl_add_u64 v[224:225], s[36:37], 0, v[128:129]
	s_mov_b32 m0, s29
	s_nop 0
	global_load_lds_dwordx4 v[224:225], off
	s_mov_b32 m0, s33
	s_nop 0
	global_load_lds_dwordx4 v[226:227], off
	s_cmp_eq_u32 s84, 0
	s_cbranch_scc1 .Lrxu2_s
	s_waitcnt vmcnt(22)
	s_mov_b32 s84, 0
	s_branch .Lrxu2_d

.Lrxu2_d:
	s_waitcnt lgkmcnt(0)
	s_barrier
	s_setprio 1
	s_waitcnt lgkmcnt(0)
	v_mfma_f32_16x16x32_bf16 v[60:63], v[156:159], v[190:193], v[60:63]
	v_mfma_f32_16x16x32_bf16 v[56:59], v[164:167], v[190:193], v[56:59]
	v_mfma_f32_16x16x32_bf16 v[44:47], v[156:159], v[198:201], v[44:47]
	v_mfma_f32_16x16x32_bf16 v[40:43], v[164:167], v[198:201], v[40:43]
	v_mfma_f32_16x16x32_bf16 v[28:31], v[156:159], v[206:209], v[28:31]
	v_mfma_f32_16x16x32_bf16 v[24:27], v[164:167], v[206:209], v[24:27]
	v_mfma_f32_16x16x32_bf16 v[12:15], v[156:159], v[214:217], v[12:15]
	v_mfma_f32_16x16x32_bf16 v[8:11], v[164:167], v[214:217], v[8:11]
	v_mfma_f32_16x16x32_bf16 v[60:63], v[160:163], v[194:197], v[60:63]
	v_mfma_f32_16x16x32_bf16 v[56:59], v[168:171], v[194:197], v[56:59]
	v_mfma_f32_16x16x32_bf16 v[44:47], v[160:163], v[202:205], v[44:47]
	v_mfma_f32_16x16x32_bf16 v[40:43], v[168:171], v[202:205], v[40:43]
	v_mfma_f32_16x16x32_bf16 v[28:31], v[160:163], v[210:213], v[28:31]
	v_mfma_f32_16x16x32_bf16 v[24:27], v[168:171], v[210:213], v[24:27]
	v_mfma_f32_16x16x32_bf16 v[12:15], v[160:163], v[218:221], v[12:15]
	v_mfma_f32_16x16x32_bf16 v[8:11], v[168:171], v[218:221], v[8:11]
	s_setprio 0
	s_setprio 1
	v_mfma_f32_16x16x32_bf16 v[52:55], v[172:175], v[190:193], v[52:55]
	v_mfma_f32_16x16x32_bf16 v[48:51], v[182:185], v[190:193], v[48:51]
	v_mfma_f32_16x16x32_bf16 v[36:39], v[172:175], v[198:201], v[36:39]
	v_mfma_f32_16x16x32_bf16 v[32:35], v[182:185], v[198:201], v[32:35]
	v_mfma_f32_16x16x32_bf16 v[20:23], v[172:175], v[206:209], v[20:23]
	v_mfma_f32_16x16x32_bf16 v[16:19], v[182:185], v[206:209], v[16:19]
	v_mfma_f32_16x16x32_bf16 v[4:7], v[172:175], v[214:217], v[4:7]
	v_mfma_f32_16x16x32_bf16 v[0:3], v[182:185], v[214:217], v[0:3]
	v_mfma_f32_16x16x32_bf16 v[52:55], v[178:181], v[194:197], v[52:55]
	v_mfma_f32_16x16x32_bf16 v[48:51], v[186:189], v[194:197], v[48:51]
	v_mfma_f32_16x16x32_bf16 v[36:39], v[178:181], v[202:205], v[36:39]
	v_mfma_f32_16x16x32_bf16 v[32:35], v[186:189], v[202:205], v[32:35]
	v_mfma_f32_16x16x32_bf16 v[20:23], v[178:181], v[210:213], v[20:23]
	v_mfma_f32_16x16x32_bf16 v[16:19], v[186:189], v[210:213], v[16:19]
	v_mfma_f32_16x16x32_bf16 v[4:7], v[178:181], v[218:221], v[4:7]
	v_mfma_f32_16x16x32_bf16 v[0:3], v[186:189], v[218:221], v[0:3]
	s_setprio 0
	s_barrier
	ds_read_b128 v[156:159], v153
	ds_read_b128 v[160:163], v153 offset:1024
	ds_read_b128 v[164:167], v153 offset:2048
	ds_read_b128 v[168:171], v153 offset:3072
	ds_read_b128 v[172:175], v154
	ds_read_b128 v[178:181], v154 offset:1024
	ds_read_b128 v[182:185], v154 offset:2048
	ds_read_b128 v[186:189], v154 offset:3072
	s_add_u32 s36, s36, 0x40000
	s_addc_u32 s37, s37, 0
	s_mov_b32 m0, s38
	v_lshl_add_u64 v[228:229], s[36:37], 0, v[128:129]
	ds_read_b128 v[190:193], v152 offset:32768
	ds_read_b128 v[194:197], v152 offset:33792
	ds_read_b128 v[198:201], v152 offset:34816
	ds_read_b128 v[202:205], v152 offset:35840
	ds_read_b128 v[206:209], v152 offset:36864
	ds_read_b128 v[210:213], v152 offset:37888
	ds_read_b128 v[214:217], v152 offset:38912
	ds_read_b128 v[218:221], v152 offset:39936
	global_load_lds_dwordx4 v[228:229], off
	v_lshl_add_u64 v[228:229], s[36:37], 0, v[132:133]
	s_mov_b32 m0, s39
	s_nop 0
	global_load_lds_dwordx4 v[228:229], off
	s_waitcnt vmcnt(8)
	s_waitcnt lgkmcnt(0)
	s_barrier
	s_setprio 1
	s_waitcnt lgkmcnt(0)
	v_mfma_f32_16x16x32_bf16 v[124:127], v[156:159], v[190:193], v[124:127]
	v_mfma_f32_16x16x32_bf16 v[120:123], v[164:167], v[190:193], v[120:123]
	v_mfma_f32_16x16x32_bf16 v[108:111], v[156:159], v[198:201], v[108:111]
	v_mfma_f32_16x16x32_bf16 v[104:107], v[164:167], v[198:201], v[104:107]
	v_mfma_f32_16x16x32_bf16 v[92:95], v[156:159], v[206:209], v[92:95]
	v_mfma_f32_16x16x32_bf16 v[88:91], v[164:167], v[206:209], v[88:91]
	v_mfma_f32_16x16x32_bf16 v[76:79], v[156:159], v[214:217], v[76:79]
	v_mfma_f32_16x16x32_bf16 v[72:75], v[164:167], v[214:217], v[72:75]
	v_mfma_f32_16x16x32_bf16 v[124:127], v[160:163], v[194:197], v[124:127]
	v_mfma_f32_16x16x32_bf16 v[120:123], v[168:171], v[194:197], v[120:123]
	v_mfma_f32_16x16x32_bf16 v[108:111], v[160:163], v[202:205], v[108:111]
	v_mfma_f32_16x16x32_bf16 v[104:107], v[168:171], v[202:205], v[104:107]
	v_mfma_f32_16x16x32_bf16 v[92:95], v[160:163], v[210:213], v[92:95]
	v_mfma_f32_16x16x32_bf16 v[88:91], v[168:171], v[210:213], v[88:91]
	v_mfma_f32_16x16x32_bf16 v[76:79], v[160:163], v[218:221], v[76:79]
	v_mfma_f32_16x16x32_bf16 v[72:75], v[168:171], v[218:221], v[72:75]
	s_setprio 0
	s_setprio 1
	v_mfma_f32_16x16x32_bf16 v[116:119], v[172:175], v[190:193], v[116:119]
	v_mfma_f32_16x16x32_bf16 v[112:115], v[182:185], v[190:193], v[112:115]
	v_mfma_f32_16x16x32_bf16 v[100:103], v[172:175], v[198:201], v[100:103]
	v_mfma_f32_16x16x32_bf16 v[96:99], v[182:185], v[198:201], v[96:99]
	v_mfma_f32_16x16x32_bf16 v[84:87], v[172:175], v[206:209], v[84:87]
	v_mfma_f32_16x16x32_bf16 v[80:83], v[182:185], v[206:209], v[80:83]
	v_mfma_f32_16x16x32_bf16 v[68:71], v[172:175], v[214:217], v[68:71]
	v_mfma_f32_16x16x32_bf16 v[64:67], v[182:185], v[214:217], v[64:67]
	v_mfma_f32_16x16x32_bf16 v[116:119], v[178:181], v[194:197], v[116:119]
	v_mfma_f32_16x16x32_bf16 v[112:115], v[186:189], v[194:197], v[112:115]
	v_mfma_f32_16x16x32_bf16 v[100:103], v[178:181], v[202:205], v[100:103]
	v_mfma_f32_16x16x32_bf16 v[96:99], v[186:189], v[202:205], v[96:99]
	v_mfma_f32_16x16x32_bf16 v[84:87], v[178:181], v[210:213], v[84:87]
	v_mfma_f32_16x16x32_bf16 v[80:83], v[186:189], v[210:213], v[80:83]
	v_mfma_f32_16x16x32_bf16 v[68:71], v[178:181], v[218:221], v[68:71]
	v_mfma_f32_16x16x32_bf16 v[64:67], v[186:189], v[218:221], v[64:67]
	s_setprio 0
	s_barrier
	s_add_i32 s36, s47, s3
	v_lshl_add_u64 v[144:145], v[144:145], 0, s[12:13]
	s_mov_b32 m0, s36
	ds_read_b128 v[190:193], v152 offset:49152
	ds_read_b128 v[194:197], v152 offset:50176
	ds_read_b128 v[198:201], v152 offset:51200
	ds_read_b128 v[202:205], v152 offset:52224
	ds_read_b128 v[206:209], v152 offset:53248
	ds_read_b128 v[210:213], v152 offset:54272
	ds_read_b128 v[214:217], v152 offset:55296
	ds_read_b128 v[218:221], v152 offset:56320
	global_load_lds_dwordx4 v[144:145], off
	s_add_i32 m0, s36, 0x2000
	s_add_u32 s34, s34, 0x40080
	v_lshl_add_u64 v[144:145], v[222:223], 0, s[12:13]
	s_addc_u32 s35, s35, 0
	s_add_i32 s36, s48, s3
	global_load_lds_dwordx4 v[144:145], off
	v_lshl_add_u64 v[144:145], s[34:35], 0, v[130:131]
	s_mov_b32 m0, s36
	s_nop 0
	global_load_lds_dwordx4 v[144:145], off
	v_lshl_add_u64 v[144:145], s[34:35], 0, v[134:135]
	s_add_i32 m0, s36, 0x2000
	s_nop 0
	global_load_lds_dwordx4 v[144:145], off
	v_lshl_add_u64 v[144:145], v[224:225], 0, s[12:13]
	s_mov_b32 m0, s40
	s_nop 0
	global_load_lds_dwordx4 v[144:145], off
	v_lshl_add_u64 v[144:145], v[226:227], 0, s[12:13]
	s_mov_b32 m0, s41
	s_nop 0
	global_load_lds_dwordx4 v[144:145], off
	s_waitcnt vmcnt(8)
	s_waitcnt lgkmcnt(0)
	s_barrier
	s_setprio 1
	s_waitcnt lgkmcnt(0)
	v_mfma_f32_16x16x32_bf16 v[60:63], v[156:159], v[190:193], v[60:63]
	v_mfma_f32_16x16x32_bf16 v[56:59], v[164:167], v[190:193], v[56:59]
	v_mfma_f32_16x16x32_bf16 v[44:47], v[156:159], v[198:201], v[44:47]
	v_mfma_f32_16x16x32_bf16 v[40:43], v[164:167], v[198:201], v[40:43]
	v_mfma_f32_16x16x32_bf16 v[28:31], v[156:159], v[206:209], v[28:31]
	v_mfma_f32_16x16x32_bf16 v[24:27], v[164:167], v[206:209], v[24:27]
	v_mfma_f32_16x16x32_bf16 v[12:15], v[156:159], v[214:217], v[12:15]
	v_mfma_f32_16x16x32_bf16 v[8:11], v[164:167], v[214:217], v[8:11]
	v_mfma_f32_16x16x32_bf16 v[60:63], v[160:163], v[194:197], v[60:63]
	v_mfma_f32_16x16x32_bf16 v[56:59], v[168:171], v[194:197], v[56:59]
	v_mfma_f32_16x16x32_bf16 v[44:47], v[160:163], v[202:205], v[44:47]
	v_mfma_f32_16x16x32_bf16 v[40:43], v[168:171], v[202:205], v[40:43]
	v_mfma_f32_16x16x32_bf16 v[28:31], v[160:163], v[210:213], v[28:31]
	v_mfma_f32_16x16x32_bf16 v[24:27], v[168:171], v[210:213], v[24:27]
	v_mfma_f32_16x16x32_bf16 v[12:15], v[160:163], v[218:221], v[12:15]
	v_mfma_f32_16x16x32_bf16 v[8:11], v[168:171], v[218:221], v[8:11]
	s_setprio 0
	s_setprio 1
	v_mfma_f32_16x16x32_bf16 v[52:55], v[172:175], v[190:193], v[52:55]
	v_mfma_f32_16x16x32_bf16 v[48:51], v[182:185], v[190:193], v[48:51]
	v_mfma_f32_16x16x32_bf16 v[36:39], v[172:175], v[198:201], v[36:39]
	v_mfma_f32_16x16x32_bf16 v[32:35], v[182:185], v[198:201], v[32:35]
	v_mfma_f32_16x16x32_bf16 v[20:23], v[172:175], v[206:209], v[20:23]
	v_mfma_f32_16x16x32_bf16 v[16:19], v[182:185], v[206:209], v[16:19]
	v_mfma_f32_16x16x32_bf16 v[4:7], v[172:175], v[214:217], v[4:7]
	v_mfma_f32_16x16x32_bf16 v[0:3], v[182:185], v[214:217], v[0:3]
	v_mfma_f32_16x16x32_bf16 v[52:55], v[178:181], v[194:197], v[52:55]
	v_mfma_f32_16x16x32_bf16 v[48:51], v[186:189], v[194:197], v[48:51]
	v_mfma_f32_16x16x32_bf16 v[36:39], v[178:181], v[202:205], v[36:39]
	v_mfma_f32_16x16x32_bf16 v[32:35], v[186:189], v[202:205], v[32:35]
	v_mfma_f32_16x16x32_bf16 v[20:23], v[178:181], v[210:213], v[20:23]
	v_mfma_f32_16x16x32_bf16 v[16:19], v[186:189], v[210:213], v[16:19]
	v_mfma_f32_16x16x32_bf16 v[4:7], v[178:181], v[218:221], v[4:7]
	v_mfma_f32_16x16x32_bf16 v[0:3], v[186:189], v[218:221], v[0:3]
	s_setprio 0
	s_barrier
	s_add_i32 s54, s54, 2
	s_add_u32 s30, s30, 0x100
	s_addc_u32 s31, s31, 0
	s_add_u32 s52, s52, 0x100
	s_addc_u32 s53, s53, 0
	s_cmp_gt_u32 s54, 13
	s_cbranch_scc0 .LBB0_1079
	s_and_b64 vcc, exec, s[0:1]
	s_cbranch_vccz .LBB0_1082
	s_barrier

.Lgd5_skip:
	ds_read_b32 v156, v147
	v_lshl_add_u32 v144, s28, 8, v146
	v_lshl_or_b32 v158, s49, 8, v149
	v_ashrrev_i32_e32 v145, 31, v144
	v_lshlrev_b64 v[160:161], 13, v[144:145]
	s_waitcnt lgkmcnt(0)
	v_pk_mul_f32 v[126:127], v[126:127], v[156:157] op_sel_hi:[1,0]
	v_pk_mul_f32 v[124:125], v[124:125], v[156:157] op_sel_hi:[1,0]
	v_pk_mul_f32 v[122:123], v[122:123], v[156:157] op_sel_hi:[1,0]
	v_pk_mul_f32 v[120:121], v[120:121], v[156:157] op_sel_hi:[1,0]
	v_max_f32_e32 v124, 0, v124
	v_max_f32_e32 v126, 0, v126
	v_max_f32_e32 v127, 0, v127
	v_max_f32_e32 v120, 0, v120
	v_max_f32_e32 v121, 0, v121
	v_max_f32_e32 v122, 0, v122
	v_mul_f32_e32 v124, v124, v124
	v_max_f32_e32 v125, 0, v125
	v_mul_f32_e32 v126, v126, v126
	v_mul_f32_e32 v127, v127, v127
	v_mul_f32_e32 v120, v120, v120
	v_mul_f32_e32 v121, v121, v121
	v_mul_f32_e32 v145, v122, v122
	v_max_f32_e32 v122, 0, v123
	v_ashrrev_i32_e32 v159, 31, v158
	v_mul_f32_e32 v125, v125, v125
	v_mul_f32_e32 v155, v122, v122
	v_cvt_pk_bf16_f32 v122, v124, v125
	v_cvt_pk_bf16_f32 v123, v126, v127
	v_cvt_pk_bf16_f32 v124, v120, v121
	v_lshl_add_u64 v[126:127], s[14:15], 0, v[160:161]
	v_lshlrev_b64 v[120:121], 1, v[158:159]
	v_pk_mul_f32 v[112:113], v[112:113], v[156:157] op_sel_hi:[1,0]
	v_lshl_add_u64 v[126:127], v[126:127], 0, v[120:121]
	v_max_f32_e32 v112, 0, v112
	v_cvt_pk_bf16_f32 v125, v145, v155
	global_store_dwordx4 v[126:127], v[122:125], off
	v_pk_mul_f32 v[114:115], v[114:115], v[156:157] op_sel_hi:[1,0]
	v_pk_mul_f32 v[116:117], v[116:117], v[156:157] op_sel_hi:[1,0]
	v_mul_f32_e32 v122, v112, v112
	v_max_f32_e32 v112, 0, v113
	v_mul_f32_e32 v123, v112, v112
	v_max_f32_e32 v112, 0, v114
	v_pk_mul_f32 v[118:119], v[118:119], v[156:157] op_sel_hi:[1,0]
	v_max_f32_e32 v116, 0, v116
	v_mul_f32_e32 v124, v112, v112
	v_max_f32_e32 v112, 0, v115
	v_mul_f32_e32 v116, v116, v116
	v_max_f32_e32 v117, 0, v117
	v_max_f32_e32 v118, 0, v118
	v_max_f32_e32 v119, 0, v119
	v_mul_f32_e32 v115, v112, v112
	v_mul_f32_e32 v117, v117, v117
	v_mul_f32_e32 v118, v118, v118
	v_mul_f32_e32 v119, v119, v119
	v_cvt_pk_bf16_f32 v112, v116, v117
	v_cvt_pk_bf16_f32 v113, v118, v119
	v_cvt_pk_bf16_f32 v114, v122, v123
	v_cvt_pk_bf16_f32 v115, v124, v115
	ds_read_b32 v116, v147 offset:64
	global_store_dwordx4 v[126:127], v[112:115], off offset:256
	s_andn2_b64 vcc, exec, s[6:7]
	s_mov_b64 s[6:7], -1
	v_or_b32_e32 v112, 16, v144
	s_waitcnt lgkmcnt(0)
	v_pk_mul_f32 v[104:105], v[104:105], v[116:117] op_sel_hi:[1,0]
	v_pk_mul_f32 v[108:109], v[108:109], v[116:117] op_sel_hi:[1,0]
	v_max_f32_e32 v104, 0, v104
	v_pk_mul_f32 v[106:107], v[106:107], v[116:117] op_sel_hi:[1,0]
	v_mul_f32_e32 v114, v104, v104
	v_max_f32_e32 v104, 0, v105
	v_ashrrev_i32_e32 v113, 31, v112
	v_max_f32_e32 v108, 0, v108
	v_max_f32_e32 v109, 0, v109
	v_mul_f32_e32 v115, v104, v104
	v_max_f32_e32 v104, 0, v106
	v_lshlrev_b64 v[112:113], 13, v[112:113]
	v_pk_mul_f32 v[110:111], v[110:111], v[116:117] op_sel_hi:[1,0]
	v_mul_f32_e32 v108, v108, v108
	v_mul_f32_e32 v109, v109, v109
	v_mul_f32_e32 v117, v104, v104
	v_max_f32_e32 v104, 0, v107
	v_mul_f32_e32 v107, v104, v104
	v_cvt_pk_bf16_f32 v104, v108, v109
	v_lshl_add_u64 v[108:109], s[14:15], 0, v[112:113]
	v_pk_mul_f32 v[96:97], v[96:97], v[116:117] op_sel_hi:[1,0]
	v_max_f32_e32 v110, 0, v110
	v_max_f32_e32 v111, 0, v111
	v_lshl_add_u64 v[108:109], v[108:109], 0, v[120:121]
	v_max_f32_e32 v96, 0, v96
	v_mul_f32_e32 v110, v110, v110
	v_mul_f32_e32 v111, v111, v111
	v_cvt_pk_bf16_f32 v105, v110, v111
	v_cvt_pk_bf16_f32 v106, v114, v115
	v_cvt_pk_bf16_f32 v107, v117, v107
	global_store_dwordx4 v[108:109], v[104:107], off
	v_pk_mul_f32 v[98:99], v[98:99], v[116:117] op_sel_hi:[1,0]
	v_pk_mul_f32 v[100:101], v[100:101], v[116:117] op_sel_hi:[1,0]
	v_mul_f32_e32 v104, v96, v96
	v_max_f32_e32 v96, 0, v97
	v_mul_f32_e32 v105, v96, v96
	v_max_f32_e32 v96, 0, v98
	v_pk_mul_f32 v[102:103], v[102:103], v[116:117] op_sel_hi:[1,0]
	v_max_f32_e32 v100, 0, v100
	v_mul_f32_e32 v106, v96, v96
	v_max_f32_e32 v96, 0, v99
	v_mul_f32_e32 v100, v100, v100
	v_max_f32_e32 v101, 0, v101
	v_max_f32_e32 v102, 0, v102
	v_max_f32_e32 v103, 0, v103
	v_mul_f32_e32 v99, v96, v96
	v_mul_f32_e32 v101, v101, v101
	v_mul_f32_e32 v102, v102, v102
	v_mul_f32_e32 v103, v103, v103
	v_cvt_pk_bf16_f32 v96, v100, v101
	v_cvt_pk_bf16_f32 v97, v102, v103
	v_cvt_pk_bf16_f32 v98, v104, v105
	v_cvt_pk_bf16_f32 v99, v106, v99
	ds_read_b32 v100, v147 offset:128
	global_store_dwordx4 v[108:109], v[96:99], off offset:256
	s_waitcnt lgkmcnt(0)
	v_pk_mul_f32 v[88:89], v[88:89], v[100:101] op_sel_hi:[1,0]
	s_nop 0
	v_max_f32_e32 v88, 0, v88
	v_or_b32_e32 v96, 32, v144
	v_pk_mul_f32 v[92:93], v[92:93], v[100:101] op_sel_hi:[1,0]
	v_pk_mul_f32 v[90:91], v[90:91], v[100:101] op_sel_hi:[1,0]
	v_mul_f32_e32 v98, v88, v88
	v_max_f32_e32 v88, 0, v89
	v_ashrrev_i32_e32 v97, 31, v96
	v_max_f32_e32 v92, 0, v92
	v_max_f32_e32 v93, 0, v93
	v_mul_f32_e32 v99, v88, v88
	v_max_f32_e32 v88, 0, v90
	v_lshlrev_b64 v[96:97], 13, v[96:97]
	v_pk_mul_f32 v[94:95], v[94:95], v[100:101] op_sel_hi:[1,0]
	v_mul_f32_e32 v92, v92, v92
	v_mul_f32_e32 v93, v93, v93
	v_mul_f32_e32 v101, v88, v88
	v_max_f32_e32 v88, 0, v91
	v_mul_f32_e32 v91, v88, v88
	v_cvt_pk_bf16_f32 v88, v92, v93
	v_lshl_add_u64 v[92:93], s[14:15], 0, v[96:97]
	v_pk_mul_f32 v[80:81], v[80:81], v[100:101] op_sel_hi:[1,0]
	v_max_f32_e32 v94, 0, v94
	v_max_f32_e32 v95, 0, v95
	v_lshl_add_u64 v[92:93], v[92:93], 0, v[120:121]
	v_max_f32_e32 v80, 0, v80
	v_mul_f32_e32 v94, v94, v94
	v_mul_f32_e32 v95, v95, v95
	v_cvt_pk_bf16_f32 v89, v94, v95
	v_cvt_pk_bf16_f32 v90, v98, v99
	v_cvt_pk_bf16_f32 v91, v101, v91
	global_store_dwordx4 v[92:93], v[88:91], off
	v_pk_mul_f32 v[82:83], v[82:83], v[100:101] op_sel_hi:[1,0]
	v_pk_mul_f32 v[84:85], v[84:85], v[100:101] op_sel_hi:[1,0]
	v_mul_f32_e32 v88, v80, v80
	v_max_f32_e32 v80, 0, v81
	v_mul_f32_e32 v89, v80, v80
	v_max_f32_e32 v80, 0, v82
	v_pk_mul_f32 v[86:87], v[86:87], v[100:101] op_sel_hi:[1,0]
	v_max_f32_e32 v84, 0, v84
	v_mul_f32_e32 v90, v80, v80
	v_max_f32_e32 v80, 0, v83
	v_mul_f32_e32 v84, v84, v84
	v_max_f32_e32 v85, 0, v85
	v_max_f32_e32 v86, 0, v86
	v_max_f32_e32 v87, 0, v87
	v_mul_f32_e32 v83, v80, v80
	v_mul_f32_e32 v85, v85, v85
	v_mul_f32_e32 v86, v86, v86
	v_mul_f32_e32 v87, v87, v87
	v_cvt_pk_bf16_f32 v80, v84, v85
	v_cvt_pk_bf16_f32 v81, v86, v87
	v_cvt_pk_bf16_f32 v82, v88, v89
	v_cvt_pk_bf16_f32 v83, v90, v83
	ds_read_b32 v84, v147 offset:192
	global_store_dwordx4 v[92:93], v[80:83], off offset:256
	s_waitcnt lgkmcnt(0)
	v_pk_mul_f32 v[72:73], v[72:73], v[84:85] op_sel_hi:[1,0]
	s_nop 0
	v_max_f32_e32 v72, 0, v72
	v_or_b32_e32 v80, 48, v144
	v_pk_mul_f32 v[76:77], v[76:77], v[84:85] op_sel_hi:[1,0]
	v_pk_mul_f32 v[74:75], v[74:75], v[84:85] op_sel_hi:[1,0]
	v_mul_f32_e32 v82, v72, v72
	v_max_f32_e32 v72, 0, v73
	v_ashrrev_i32_e32 v81, 31, v80
	v_max_f32_e32 v76, 0, v76
	v_max_f32_e32 v77, 0, v77
	v_mul_f32_e32 v83, v72, v72
	v_max_f32_e32 v72, 0, v74
	v_lshlrev_b64 v[80:81], 13, v[80:81]
	v_pk_mul_f32 v[78:79], v[78:79], v[84:85] op_sel_hi:[1,0]
	v_mul_f32_e32 v76, v76, v76
	v_mul_f32_e32 v77, v77, v77
	v_mul_f32_e32 v85, v72, v72
	v_max_f32_e32 v72, 0, v75
	v_mul_f32_e32 v75, v72, v72
	v_cvt_pk_bf16_f32 v72, v76, v77
	v_lshl_add_u64 v[76:77], s[14:15], 0, v[80:81]
	v_pk_mul_f32 v[64:65], v[64:65], v[84:85] op_sel_hi:[1,0]
	v_max_f32_e32 v78, 0, v78
	v_max_f32_e32 v79, 0, v79
	v_lshl_add_u64 v[76:77], v[76:77], 0, v[120:121]
	v_max_f32_e32 v64, 0, v64
	v_mul_f32_e32 v78, v78, v78
	v_mul_f32_e32 v79, v79, v79
	v_cvt_pk_bf16_f32 v73, v78, v79
	v_cvt_pk_bf16_f32 v74, v82, v83
	v_cvt_pk_bf16_f32 v75, v85, v75
	global_store_dwordx4 v[76:77], v[72:75], off
	v_pk_mul_f32 v[66:67], v[66:67], v[84:85] op_sel_hi:[1,0]
	v_pk_mul_f32 v[68:69], v[68:69], v[84:85] op_sel_hi:[1,0]
	v_mul_f32_e32 v72, v64, v64
	v_max_f32_e32 v64, 0, v65
	v_mul_f32_e32 v73, v64, v64
	v_max_f32_e32 v64, 0, v66
	v_pk_mul_f32 v[70:71], v[70:71], v[84:85] op_sel_hi:[1,0]
	v_max_f32_e32 v68, 0, v68
	v_mul_f32_e32 v74, v64, v64
	v_max_f32_e32 v64, 0, v67
	v_mul_f32_e32 v68, v68, v68
	v_max_f32_e32 v69, 0, v69
	v_max_f32_e32 v70, 0, v70
	v_max_f32_e32 v71, 0, v71
	v_mul_f32_e32 v67, v64, v64
	v_mul_f32_e32 v69, v69, v69
	v_mul_f32_e32 v70, v70, v70
	v_mul_f32_e32 v71, v71, v71
	v_cvt_pk_bf16_f32 v64, v68, v69
	v_cvt_pk_bf16_f32 v65, v70, v71
	v_cvt_pk_bf16_f32 v66, v72, v73
	v_cvt_pk_bf16_f32 v67, v74, v67
	ds_read_b32 v68, v148
	global_store_dwordx4 v[76:77], v[64:67], off offset:256
	s_waitcnt lgkmcnt(0)
	v_pk_mul_f32 v[56:57], v[56:57], v[68:69] op_sel_hi:[1,0]
	s_nop 0
	v_max_f32_e32 v56, 0, v56
	v_add_u32_e32 v64, 0x80, v144
	v_pk_mul_f32 v[60:61], v[60:61], v[68:69] op_sel_hi:[1,0]
	v_pk_mul_f32 v[58:59], v[58:59], v[68:69] op_sel_hi:[1,0]
	v_mul_f32_e32 v66, v56, v56
	v_max_f32_e32 v56, 0, v57
	v_ashrrev_i32_e32 v65, 31, v64
	v_max_f32_e32 v60, 0, v60
	v_max_f32_e32 v61, 0, v61
	v_mul_f32_e32 v67, v56, v56
	v_max_f32_e32 v56, 0, v58
	v_lshlrev_b64 v[64:65], 13, v[64:65]
	v_pk_mul_f32 v[62:63], v[62:63], v[68:69] op_sel_hi:[1,0]
	v_mul_f32_e32 v60, v60, v60
	v_mul_f32_e32 v61, v61, v61
	v_mul_f32_e32 v69, v56, v56
	v_max_f32_e32 v56, 0, v59
	v_mul_f32_e32 v59, v56, v56
	v_cvt_pk_bf16_f32 v56, v60, v61
	v_lshl_add_u64 v[60:61], s[14:15], 0, v[64:65]
	v_pk_mul_f32 v[48:49], v[48:49], v[68:69] op_sel_hi:[1,0]
	v_max_f32_e32 v62, 0, v62
	v_max_f32_e32 v63, 0, v63
	v_lshl_add_u64 v[60:61], v[60:61], 0, v[120:121]
	v_max_f32_e32 v48, 0, v48
	v_mul_f32_e32 v62, v62, v62
	v_mul_f32_e32 v63, v63, v63
	v_cvt_pk_bf16_f32 v57, v62, v63
	v_cvt_pk_bf16_f32 v58, v66, v67
	v_cvt_pk_bf16_f32 v59, v69, v59
	global_store_dwordx4 v[60:61], v[56:59], off
	v_pk_mul_f32 v[50:51], v[50:51], v[68:69] op_sel_hi:[1,0]
	v_pk_mul_f32 v[52:53], v[52:53], v[68:69] op_sel_hi:[1,0]
	v_mul_f32_e32 v56, v48, v48
	v_max_f32_e32 v48, 0, v49
	v_mul_f32_e32 v57, v48, v48
	v_max_f32_e32 v48, 0, v50
	v_pk_mul_f32 v[54:55], v[54:55], v[68:69] op_sel_hi:[1,0]
	v_max_f32_e32 v52, 0, v52
	v_mul_f32_e32 v58, v48, v48
	v_max_f32_e32 v48, 0, v51
	v_mul_f32_e32 v52, v52, v52
	v_max_f32_e32 v53, 0, v53
	v_max_f32_e32 v54, 0, v54
	v_max_f32_e32 v55, 0, v55
	v_mul_f32_e32 v51, v48, v48
	v_mul_f32_e32 v53, v53, v53
	v_mul_f32_e32 v54, v54, v54
	v_mul_f32_e32 v55, v55, v55
	v_cvt_pk_bf16_f32 v48, v52, v53
	v_cvt_pk_bf16_f32 v49, v54, v55
	v_cvt_pk_bf16_f32 v50, v56, v57
	v_cvt_pk_bf16_f32 v51, v58, v51
	ds_read_b32 v52, v147 offset:576
	global_store_dwordx4 v[60:61], v[48:51], off offset:256
	s_waitcnt lgkmcnt(0)
	v_pk_mul_f32 v[40:41], v[40:41], v[52:53] op_sel_hi:[1,0]
	s_nop 0
	v_max_f32_e32 v40, 0, v40
	v_add_u32_e32 v48, 0x90, v144
	v_pk_mul_f32 v[44:45], v[44:45], v[52:53] op_sel_hi:[1,0]
	v_pk_mul_f32 v[42:43], v[42:43], v[52:53] op_sel_hi:[1,0]
	v_mul_f32_e32 v50, v40, v40
	v_max_f32_e32 v40, 0, v41
	v_ashrrev_i32_e32 v49, 31, v48
	v_max_f32_e32 v44, 0, v44
	v_max_f32_e32 v45, 0, v45
	v_mul_f32_e32 v51, v40, v40
	v_max_f32_e32 v40, 0, v42
	v_lshlrev_b64 v[48:49], 13, v[48:49]
	v_pk_mul_f32 v[46:47], v[46:47], v[52:53] op_sel_hi:[1,0]
	v_mul_f32_e32 v44, v44, v44
	v_mul_f32_e32 v45, v45, v45
	v_mul_f32_e32 v53, v40, v40
	v_max_f32_e32 v40, 0, v43
	v_mul_f32_e32 v43, v40, v40
	v_cvt_pk_bf16_f32 v40, v44, v45
	v_lshl_add_u64 v[44:45], s[14:15], 0, v[48:49]
	v_pk_mul_f32 v[32:33], v[32:33], v[52:53] op_sel_hi:[1,0]
	v_max_f32_e32 v46, 0, v46
	v_max_f32_e32 v47, 0, v47
	v_lshl_add_u64 v[44:45], v[44:45], 0, v[120:121]
	v_max_f32_e32 v32, 0, v32
	v_mul_f32_e32 v46, v46, v46
	v_mul_f32_e32 v47, v47, v47
	v_cvt_pk_bf16_f32 v41, v46, v47
	v_cvt_pk_bf16_f32 v42, v50, v51
	v_cvt_pk_bf16_f32 v43, v53, v43
	global_store_dwordx4 v[44:45], v[40:43], off
	v_pk_mul_f32 v[34:35], v[34:35], v[52:53] op_sel_hi:[1,0]
	v_pk_mul_f32 v[36:37], v[36:37], v[52:53] op_sel_hi:[1,0]
	v_mul_f32_e32 v40, v32, v32
	v_max_f32_e32 v32, 0, v33
	v_mul_f32_e32 v41, v32, v32
	v_max_f32_e32 v32, 0, v34
	v_pk_mul_f32 v[38:39], v[38:39], v[52:53] op_sel_hi:[1,0]
	v_max_f32_e32 v36, 0, v36
	v_mul_f32_e32 v42, v32, v32
	v_max_f32_e32 v32, 0, v35
	v_mul_f32_e32 v36, v36, v36
	v_max_f32_e32 v37, 0, v37
	v_max_f32_e32 v38, 0, v38
	v_max_f32_e32 v39, 0, v39
	v_mul_f32_e32 v35, v32, v32
	v_mul_f32_e32 v37, v37, v37
	v_mul_f32_e32 v38, v38, v38
	v_mul_f32_e32 v39, v39, v39
	v_cvt_pk_bf16_f32 v32, v36, v37
	v_cvt_pk_bf16_f32 v33, v38, v39
	v_cvt_pk_bf16_f32 v34, v40, v41
	v_cvt_pk_bf16_f32 v35, v42, v35
	ds_read_b32 v36, v147 offset:640
	global_store_dwordx4 v[44:45], v[32:35], off offset:256
	s_waitcnt lgkmcnt(0)
	v_pk_mul_f32 v[24:25], v[24:25], v[36:37] op_sel_hi:[1,0]
	s_nop 0
	v_max_f32_e32 v24, 0, v24
	v_add_u32_e32 v32, 0xa0, v144
	v_pk_mul_f32 v[28:29], v[28:29], v[36:37] op_sel_hi:[1,0]
	v_pk_mul_f32 v[26:27], v[26:27], v[36:37] op_sel_hi:[1,0]
	v_mul_f32_e32 v34, v24, v24
	v_max_f32_e32 v24, 0, v25
	v_ashrrev_i32_e32 v33, 31, v32
	v_max_f32_e32 v28, 0, v28
	v_max_f32_e32 v29, 0, v29
	v_mul_f32_e32 v35, v24, v24
	v_max_f32_e32 v24, 0, v26
	v_lshlrev_b64 v[32:33], 13, v[32:33]
	v_pk_mul_f32 v[30:31], v[30:31], v[36:37] op_sel_hi:[1,0]
	v_mul_f32_e32 v28, v28, v28
	v_mul_f32_e32 v29, v29, v29
	v_mul_f32_e32 v37, v24, v24
	v_max_f32_e32 v24, 0, v27
	v_mul_f32_e32 v27, v24, v24
	v_cvt_pk_bf16_f32 v24, v28, v29
	v_lshl_add_u64 v[28:29], s[14:15], 0, v[32:33]
	v_pk_mul_f32 v[16:17], v[16:17], v[36:37] op_sel_hi:[1,0]
	v_max_f32_e32 v30, 0, v30
	v_max_f32_e32 v31, 0, v31
	v_lshl_add_u64 v[28:29], v[28:29], 0, v[120:121]
	v_max_f32_e32 v16, 0, v16
	v_mul_f32_e32 v30, v30, v30
	v_mul_f32_e32 v31, v31, v31
	v_cvt_pk_bf16_f32 v25, v30, v31
	v_cvt_pk_bf16_f32 v26, v34, v35
	v_cvt_pk_bf16_f32 v27, v37, v27
	global_store_dwordx4 v[28:29], v[24:27], off
	v_pk_mul_f32 v[18:19], v[18:19], v[36:37] op_sel_hi:[1,0]
	v_pk_mul_f32 v[20:21], v[20:21], v[36:37] op_sel_hi:[1,0]
	v_mul_f32_e32 v24, v16, v16
	v_max_f32_e32 v16, 0, v17
	v_mul_f32_e32 v25, v16, v16
	v_max_f32_e32 v16, 0, v18
	v_pk_mul_f32 v[22:23], v[22:23], v[36:37] op_sel_hi:[1,0]
	v_max_f32_e32 v20, 0, v20
	v_mul_f32_e32 v26, v16, v16
	v_max_f32_e32 v16, 0, v19
	v_mul_f32_e32 v20, v20, v20
	v_max_f32_e32 v21, 0, v21
	v_max_f32_e32 v22, 0, v22
	v_max_f32_e32 v23, 0, v23
	v_mul_f32_e32 v19, v16, v16
	v_mul_f32_e32 v21, v21, v21
	v_mul_f32_e32 v22, v22, v22
	v_mul_f32_e32 v23, v23, v23
	v_cvt_pk_bf16_f32 v16, v20, v21
	v_cvt_pk_bf16_f32 v17, v22, v23
	v_cvt_pk_bf16_f32 v18, v24, v25
	v_cvt_pk_bf16_f32 v19, v26, v19
	ds_read_b32 v20, v147 offset:704
	global_store_dwordx4 v[28:29], v[16:19], off offset:256
	s_waitcnt lgkmcnt(0)
	v_pk_mul_f32 v[8:9], v[8:9], v[20:21] op_sel_hi:[1,0]
	s_nop 0
	v_max_f32_e32 v8, 0, v8
	v_add_u32_e32 v16, 0xb0, v144
	v_pk_mul_f32 v[12:13], v[12:13], v[20:21] op_sel_hi:[1,0]
	v_pk_mul_f32 v[10:11], v[10:11], v[20:21] op_sel_hi:[1,0]
	v_mul_f32_e32 v18, v8, v8
	v_max_f32_e32 v8, 0, v9
	v_ashrrev_i32_e32 v17, 31, v16
	v_max_f32_e32 v12, 0, v12
	v_max_f32_e32 v13, 0, v13
	v_mul_f32_e32 v19, v8, v8
	v_max_f32_e32 v8, 0, v10
	v_lshlrev_b64 v[16:17], 13, v[16:17]
	v_pk_mul_f32 v[14:15], v[14:15], v[20:21] op_sel_hi:[1,0]
	v_mul_f32_e32 v12, v12, v12
	v_mul_f32_e32 v13, v13, v13
	v_mul_f32_e32 v21, v8, v8
	v_max_f32_e32 v8, 0, v11
	v_mul_f32_e32 v11, v8, v8
	v_cvt_pk_bf16_f32 v8, v12, v13
	v_lshl_add_u64 v[12:13], s[14:15], 0, v[16:17]
	v_pk_mul_f32 v[0:1], v[0:1], v[20:21] op_sel_hi:[1,0]
	v_max_f32_e32 v14, 0, v14
	v_max_f32_e32 v15, 0, v15
	v_lshl_add_u64 v[12:13], v[12:13], 0, v[120:121]
	v_max_f32_e32 v0, 0, v0
	v_mul_f32_e32 v14, v14, v14
	v_mul_f32_e32 v15, v15, v15
	v_cvt_pk_bf16_f32 v9, v14, v15
	v_cvt_pk_bf16_f32 v10, v18, v19
	v_cvt_pk_bf16_f32 v11, v21, v11
	global_store_dwordx4 v[12:13], v[8:11], off
	v_pk_mul_f32 v[2:3], v[2:3], v[20:21] op_sel_hi:[1,0]
	v_pk_mul_f32 v[6:7], v[6:7], v[20:21] op_sel_hi:[1,0]
	v_mul_f32_e32 v8, v0, v0
	v_max_f32_e32 v0, 0, v1
	v_mul_f32_e32 v9, v0, v0
	v_max_f32_e32 v0, 0, v2
	v_pk_mul_f32 v[4:5], v[4:5], v[20:21] op_sel_hi:[1,0]
	v_mul_f32_e32 v10, v0, v0
	v_max_f32_e32 v0, 0, v3
	v_max_f32_e32 v4, 0, v4
	v_max_f32_e32 v5, 0, v5
	v_max_f32_e32 v6, 0, v6
	v_max_f32_e32 v7, 0, v7
	v_mul_f32_e32 v3, v0, v0
	v_mul_f32_e32 v4, v4, v4
	v_mul_f32_e32 v5, v5, v5
	v_mul_f32_e32 v6, v6, v6
	v_mul_f32_e32 v7, v7, v7
	v_cvt_pk_bf16_f32 v0, v4, v5
	v_cvt_pk_bf16_f32 v1, v6, v7
	v_cvt_pk_bf16_f32 v2, v8, v9
	v_cvt_pk_bf16_f32 v3, v10, v3
	global_store_dwordx4 v[12:13], v[0:3], off offset:256
	s_mov_b32 s84, 1
	s_cbranch_vccnz .LBB0_1071
	s_andn2_b64 vcc, exec, s[10:11]
	s_cbranch_vccnz .LBB0_1070
	s_barrier
	s_branch .LBB0_1070
